# P2a conv fix-up loop hand-pipelined: the three independent items of a thread issue all 33 loads first (was 2-3 serial memory latencies plus a store ack per item)
# baseline (speedup 1.0000x reference)
; __global__ void __launch_bounds__(NTHR, 2) hybrid_block_fwd(Args a) {
;     ...
;             const int c4 = (idx % (LW / 4)) * 4, rr = (idx / (LW / 4)) % 3, blk = idx / (3 * (LW / 4));
;             const bool seq0 = (blk & 127) == 0; const int pb = seq0 ? blk : blk - 1; const size_t row = (size_t)blk * 64 + rr;
;             const float* H = HEADU + (size_t)blk * 3 * LW + c4; const float* T = TAILU + (size_t)pb * 3 * LW + c4;
;             const f32x4 z = (f32x4){0.f, 0.f, 0.f, 0.f};
;             const f32x4 t0 = *(const f32x4*)(T), t1 = *(const f32x4*)(T + LW), t2 = *(const f32x4*)(T + 2 * LW);
;             const f32x4 h0 = *(const f32x4*)(H), h1 = *(const f32x4*)(H + (rr >= 1 ? LW : 0)), h2 = *(const f32x4*)(H + (rr >= 2 ? 2 * LW : 0));
;             const f32x4 T0 = seq0 ? z : t0, T1 = seq0 ? z : t1, T2 = seq0 ? z : t2;
;             const f32x4 u0 = rr == 0 ? h0 : (rr == 1 ? h1 : h2);
;             const f32x4 u1 = rr == 0 ? T2 : (rr == 1 ? h0 : h1);
;             const f32x4 u2 = rr == 0 ? T1 : (rr == 1 ? T2 : h0);
;             const f32x4 u3 = rr == 0 ? T0 : (rr == 1 ? T1 : T2);
;             const f32x4 v = *(const f32x4*)(lru_conv_b + c4) + *(const f32x4*)(lru_conv_w + c4) * u3 + *(const f32x4*)(lru_conv_w + LW + c4) * u2 + *(const f32x4*)(lru_conv_w + 2 * LW + c4) * u1 + *(const f32x4*)(lru_conv_w + 3 * LW + c4) * u0;
.LBB0_460:
	v_add_co_u32_e32 v4, vcc, 0x7000, v124
	s_mov_b32 s0, 0x60000
	s_nop 0
	v_addc_co_u32_e32 v5, vcc, 0, v125, vcc
	v_cmp_gt_i32_e32 vcc, s0, v128
	global_store_dwordx4 v[4:5], v[0:3], off offset:2048 sc1
	s_and_saveexec_b64 s[6:7], vcc
	s_cbranch_execz .LBB0_465
	v_mov_b32_e32 v210, 0x2000
	v_mov_b32_e32 v211, 0x4000
	v_mov_b32_e32 v200, v128
	v_lshrrev_b32_e32 v201, 9, v200
	v_and_b32_e32 v202, 0x1ff, v200
	v_lshlrev_b32_e32 v202, 4, v202
	v_mul_u32_u24_e32 v203, 0xaaab, v201
	v_lshrrev_b32_e32 v203, 17, v203
	v_mul_u32_u24_e32 v204, 3, v203
	v_sub_u32_e32 v204, v201, v204
	v_mov_b32_e32 v53, v204
	v_mov_b32_e32 v54, v203
	v_and_b32_e32 v205, 0x7f, v203
	v_cmp_ne_u32_e32 vcc, 0, v205
	v_mul_u32_u24_e32 v206, 0x6000, v203
	v_add_u32_e32 v206, v206, v202
	v_cndmask_b32_e64 v205, 0, 1, vcc
	v_sub_u32_e32 v205, v203, v205
	v_mul_u32_u24_e32 v207, 0x6000, v205
	v_add_u32_e32 v207, v207, v202
	global_load_dwordx4 v[8:11], v207, s[74:75]
	v_add_u32_e32 v208, 0x2000, v207
	global_load_dwordx4 v[12:15], v208, s[74:75]
	v_add_u32_e32 v209, 0x4000, v207
	global_load_dwordx4 v[16:19], v209, s[74:75]
	global_load_dwordx4 v[20:23], v206, s[50:51]
	v_cmp_lt_u32_e32 vcc, 0, v204
	s_nop 1
	v_cndmask_b32_e32 v208, 0, v210, vcc
	v_add_u32_e32 v208, v206, v208
	global_load_dwordx4 v[24:27], v208, s[50:51]
	v_cmp_lt_u32_e32 vcc, 1, v204
	s_nop 1
	v_cndmask_b32_e32 v209, 0, v211, vcc
	v_add_u32_e32 v209, v206, v209
	global_load_dwordx4 v[28:31], v209, s[50:51]
	global_load_dwordx4 v[32:35], v202, s[66:67]
	global_load_dwordx4 v[36:39], v202, s[64:65]
	global_load_dwordx4 v[40:43], v202, s[56:57]
	global_load_dwordx4 v[44:47], v202, s[60:61]
	global_load_dwordx4 v[48:51], v202, s[16:17]
	v_lshlrev_b32_e32 v208, 18, v203
	v_lshl_add_u32 v208, v204, 12, v208
	v_lshrrev_b32_e32 v209, 1, v202
	v_add_u32_e32 v52, v208, v209
	v_add_u32_e32 v200, 0x20000, v128
	v_lshrrev_b32_e32 v201, 9, v200
	v_and_b32_e32 v202, 0x1ff, v200
	v_lshlrev_b32_e32 v202, 4, v202
	v_mul_u32_u24_e32 v203, 0xaaab, v201
	v_lshrrev_b32_e32 v203, 17, v203
	v_mul_u32_u24_e32 v204, 3, v203
	v_sub_u32_e32 v204, v201, v204
	v_mov_b32_e32 v105, v204
	v_mov_b32_e32 v106, v203
	v_and_b32_e32 v205, 0x7f, v203
	v_cmp_ne_u32_e32 vcc, 0, v205
	v_mul_u32_u24_e32 v206, 0x6000, v203
	v_add_u32_e32 v206, v206, v202
	v_cndmask_b32_e64 v205, 0, 1, vcc
	v_sub_u32_e32 v205, v203, v205
	v_mul_u32_u24_e32 v207, 0x6000, v205
	v_add_u32_e32 v207, v207, v202
	global_load_dwordx4 v[60:63], v207, s[74:75]
	v_add_u32_e32 v208, 0x2000, v207
	global_load_dwordx4 v[64:67], v208, s[74:75]
	v_add_u32_e32 v209, 0x4000, v207
	global_load_dwordx4 v[68:71], v209, s[74:75]
	global_load_dwordx4 v[72:75], v206, s[50:51]
	v_cmp_lt_u32_e32 vcc, 0, v204
	s_nop 1
	v_cndmask_b32_e32 v208, 0, v210, vcc
	v_add_u32_e32 v208, v206, v208
	global_load_dwordx4 v[76:79], v208, s[50:51]
	v_cmp_lt_u32_e32 vcc, 1, v204
	s_nop 1
	v_cndmask_b32_e32 v209, 0, v211, vcc
	v_add_u32_e32 v209, v206, v209
	global_load_dwordx4 v[80:83], v209, s[50:51]
	global_load_dwordx4 v[84:87], v202, s[66:67]
	global_load_dwordx4 v[88:91], v202, s[64:65]
	global_load_dwordx4 v[92:95], v202, s[56:57]
	global_load_dwordx4 v[96:99], v202, s[60:61]
	global_load_dwordx4 v[100:103], v202, s[16:17]
	v_lshlrev_b32_e32 v208, 18, v203
	v_lshl_add_u32 v208, v204, 12, v208
	v_lshrrev_b32_e32 v209, 1, v202
	v_add_u32_e32 v104, v208, v209
	v_add_u32_e32 v200, 0x40000, v128
	v_lshrrev_b32_e32 v201, 9, v200
	v_and_b32_e32 v202, 0x1ff, v200
	v_lshlrev_b32_e32 v202, 4, v202
	v_mul_u32_u24_e32 v203, 0xaaab, v201
	v_lshrrev_b32_e32 v203, 17, v203
	v_mul_u32_u24_e32 v204, 3, v203
	v_sub_u32_e32 v204, v201, v204
	v_mov_b32_e32 v157, v204
	v_mov_b32_e32 v158, v203
	v_and_b32_e32 v205, 0x7f, v203
	v_cmp_ne_u32_e32 vcc, 0, v205
	v_mul_u32_u24_e32 v206, 0x6000, v203
	v_add_u32_e32 v206, v206, v202
	v_cndmask_b32_e64 v205, 0, 1, vcc
	v_sub_u32_e32 v205, v203, v205
	v_mul_u32_u24_e32 v207, 0x6000, v205
	v_add_u32_e32 v207, v207, v202
	global_load_dwordx4 v[112:115], v207, s[74:75]
	v_add_u32_e32 v208, 0x2000, v207
	global_load_dwordx4 v[116:119], v208, s[74:75]
	v_add_u32_e32 v209, 0x4000, v207
	global_load_dwordx4 v[120:123], v209, s[74:75]
	global_load_dwordx4 v[124:127], v206, s[50:51]
	v_cmp_lt_u32_e32 vcc, 0, v204
	s_nop 1
	v_cndmask_b32_e32 v208, 0, v210, vcc
	v_add_u32_e32 v208, v206, v208
	global_load_dwordx4 v[128:131], v208, s[50:51]
	v_cmp_lt_u32_e32 vcc, 1, v204
	s_nop 1
	v_cndmask_b32_e32 v209, 0, v211, vcc
	v_add_u32_e32 v209, v206, v209
	global_load_dwordx4 v[132:135], v209, s[50:51]
	global_load_dwordx4 v[136:139], v202, s[66:67]
	global_load_dwordx4 v[140:143], v202, s[64:65]
	global_load_dwordx4 v[144:147], v202, s[56:57]
	global_load_dwordx4 v[148:151], v202, s[60:61]
	global_load_dwordx4 v[152:155], v202, s[16:17]
	v_lshlrev_b32_e32 v208, 18, v203
	v_lshl_add_u32 v208, v204, 12, v208
	v_lshrrev_b32_e32 v209, 1, v202
	v_add_u32_e32 v156, v208, v209
	s_waitcnt vmcnt(22)
; __device__ __forceinline__ unsigned cvt_pk_bf16(float lo, float hi) { unsigned r; asm volatile("v_cvt_pk_bf16_f32 %0, %1, %2" : "=v"(r) : "v"(lo), "v"(hi)); return r; }
; __global__ void __launch_bounds__(NTHR, 2) hybrid_block_fwd(Args a) {
;     ...
;             const f32x4 h0 = *(const f32x4*)(H), h1 = *(const f32x4*)(H + (rr >= 1 ? LW : 0)), h2 = *(const f32x4*)(H + (rr >= 2 ? 2 * LW : 0));
;             const f32x4 T0 = seq0 ? z : t0, T1 = seq0 ? z : t1, T2 = seq0 ? z : t2;
;             const f32x4 u0 = rr == 0 ? h0 : (rr == 1 ? h1 : h2);
;             const f32x4 u1 = rr == 0 ? T2 : (rr == 1 ? h0 : h1);
;             const f32x4 u2 = rr == 0 ? T1 : (rr == 1 ? T2 : h0);
;             const f32x4 u3 = rr == 0 ? T0 : (rr == 1 ? T1 : T2);
;             const f32x4 v = *(const f32x4*)(lru_conv_b + c4) + *(const f32x4*)(lru_conv_w + c4) * u3 + *(const f32x4*)(lru_conv_w + LW + c4) * u2 + *(const f32x4*)(lru_conv_w + 2 * LW + c4) * u1 + *(const f32x4*)(lru_conv_w + 3 * LW + c4) * u0;
;             u32x2 w; w.x = cvt_pk_bf16(v[0], v[1]); w.y = cvt_pk_bf16(v[2], v[3]);
;             *(u32x2*)(VV + row * LW + c4) = w;
	v_and_b32_e32 v200, 0x7f, v54
	v_cmp_ne_u32_e64 s[0:1], 0, v200
	v_cmp_eq_u32_e64 s[4:5], 0, v53
	v_cmp_eq_u32_e64 s[8:9], 1, v53
	s_nop 1
	v_cndmask_b32_e64 v8, 0, v8, s[0:1]
	v_cndmask_b32_e64 v9, 0, v9, s[0:1]
	v_cndmask_b32_e64 v10, 0, v10, s[0:1]
	v_cndmask_b32_e64 v11, 0, v11, s[0:1]
	v_cndmask_b32_e64 v12, 0, v12, s[0:1]
	v_cndmask_b32_e64 v13, 0, v13, s[0:1]
	v_cndmask_b32_e64 v14, 0, v14, s[0:1]
	v_cndmask_b32_e64 v15, 0, v15, s[0:1]
	v_cndmask_b32_e64 v16, 0, v16, s[0:1]
	v_cndmask_b32_e64 v17, 0, v17, s[0:1]
	v_cndmask_b32_e64 v18, 0, v18, s[0:1]
	v_cndmask_b32_e64 v19, 0, v19, s[0:1]
	v_cndmask_b32_e64 v176, v16, v12, s[8:9]
	v_cndmask_b32_e64 v177, v17, v13, s[8:9]
	v_cndmask_b32_e64 v178, v18, v14, s[8:9]
	v_cndmask_b32_e64 v179, v19, v15, s[8:9]
	v_cndmask_b32_e64 v176, v176, v8, s[4:5]
	v_cndmask_b32_e64 v177, v177, v9, s[4:5]
	v_cndmask_b32_e64 v178, v178, v10, s[4:5]
	v_cndmask_b32_e64 v179, v179, v11, s[4:5]
	v_cndmask_b32_e64 v180, v20, v16, s[8:9]
	v_cndmask_b32_e64 v181, v21, v17, s[8:9]
	v_cndmask_b32_e64 v182, v22, v18, s[8:9]
	v_cndmask_b32_e64 v183, v23, v19, s[8:9]
	v_cndmask_b32_e64 v180, v180, v12, s[4:5]
	v_cndmask_b32_e64 v181, v181, v13, s[4:5]
	v_cndmask_b32_e64 v182, v182, v14, s[4:5]
	v_cndmask_b32_e64 v183, v183, v15, s[4:5]
	v_cndmask_b32_e64 v184, v24, v20, s[8:9]
	v_cndmask_b32_e64 v185, v25, v21, s[8:9]
	v_cndmask_b32_e64 v186, v26, v22, s[8:9]
	v_cndmask_b32_e64 v187, v27, v23, s[8:9]
	v_cndmask_b32_e64 v184, v184, v16, s[4:5]
	v_cndmask_b32_e64 v185, v185, v17, s[4:5]
	v_cndmask_b32_e64 v186, v186, v18, s[4:5]
	v_cndmask_b32_e64 v187, v187, v19, s[4:5]
	v_cndmask_b32_e64 v188, v28, v24, s[8:9]
	v_cndmask_b32_e64 v189, v29, v25, s[8:9]
	v_cndmask_b32_e64 v190, v30, v26, s[8:9]
	v_cndmask_b32_e64 v191, v31, v27, s[8:9]
	v_cndmask_b32_e64 v188, v188, v20, s[4:5]
	v_cndmask_b32_e64 v189, v189, v21, s[4:5]
	v_cndmask_b32_e64 v190, v190, v22, s[4:5]
	v_cndmask_b32_e64 v191, v191, v23, s[4:5]
	v_pk_fma_f32 v[192:193], v[176:177], v[36:37], v[32:33]
	v_pk_fma_f32 v[194:195], v[178:179], v[38:39], v[34:35]
	v_pk_fma_f32 v[192:193], v[180:181], v[40:41], v[192:193]
	v_pk_fma_f32 v[194:195], v[182:183], v[42:43], v[194:195]
	v_pk_fma_f32 v[192:193], v[184:185], v[44:45], v[192:193]
	v_pk_fma_f32 v[194:195], v[186:187], v[46:47], v[194:195]
	v_pk_fma_f32 v[192:193], v[188:189], v[48:49], v[192:193]
	v_pk_fma_f32 v[194:195], v[190:191], v[50:51], v[194:195]
	v_cvt_pk_bf16_f32 v192, v192, v193
	v_cvt_pk_bf16_f32 v193, v194, v195
	global_store_dwordx2 v52, v[192:193], s[54:55] sc1
	s_nop 1
	s_waitcnt vmcnt(12)
	v_and_b32_e32 v200, 0x7f, v106
	v_cmp_ne_u32_e64 s[0:1], 0, v200
	v_cmp_eq_u32_e64 s[4:5], 0, v105
	v_cmp_eq_u32_e64 s[8:9], 1, v105
	s_nop 1
	v_cndmask_b32_e64 v60, 0, v60, s[0:1]
	v_cndmask_b32_e64 v61, 0, v61, s[0:1]
	v_cndmask_b32_e64 v62, 0, v62, s[0:1]
	v_cndmask_b32_e64 v63, 0, v63, s[0:1]
	v_cndmask_b32_e64 v64, 0, v64, s[0:1]
	v_cndmask_b32_e64 v65, 0, v65, s[0:1]
	v_cndmask_b32_e64 v66, 0, v66, s[0:1]
	v_cndmask_b32_e64 v67, 0, v67, s[0:1]
	v_cndmask_b32_e64 v68, 0, v68, s[0:1]
	v_cndmask_b32_e64 v69, 0, v69, s[0:1]
	v_cndmask_b32_e64 v70, 0, v70, s[0:1]
	v_cndmask_b32_e64 v71, 0, v71, s[0:1]
	v_cndmask_b32_e64 v176, v68, v64, s[8:9]
	v_cndmask_b32_e64 v177, v69, v65, s[8:9]
	v_cndmask_b32_e64 v178, v70, v66, s[8:9]
	v_cndmask_b32_e64 v179, v71, v67, s[8:9]
	v_cndmask_b32_e64 v176, v176, v60, s[4:5]
	v_cndmask_b32_e64 v177, v177, v61, s[4:5]
	v_cndmask_b32_e64 v178, v178, v62, s[4:5]
	v_cndmask_b32_e64 v179, v179, v63, s[4:5]
	v_cndmask_b32_e64 v180, v72, v68, s[8:9]
	v_cndmask_b32_e64 v181, v73, v69, s[8:9]
	v_cndmask_b32_e64 v182, v74, v70, s[8:9]
	v_cndmask_b32_e64 v183, v75, v71, s[8:9]
	v_cndmask_b32_e64 v180, v180, v64, s[4:5]
	v_cndmask_b32_e64 v181, v181, v65, s[4:5]
	v_cndmask_b32_e64 v182, v182, v66, s[4:5]
	v_cndmask_b32_e64 v183, v183, v67, s[4:5]
	v_cndmask_b32_e64 v184, v76, v72, s[8:9]
	v_cndmask_b32_e64 v185, v77, v73, s[8:9]
	v_cndmask_b32_e64 v186, v78, v74, s[8:9]
	v_cndmask_b32_e64 v187, v79, v75, s[8:9]
	v_cndmask_b32_e64 v184, v184, v68, s[4:5]
	v_cndmask_b32_e64 v185, v185, v69, s[4:5]
	v_cndmask_b32_e64 v186, v186, v70, s[4:5]
	v_cndmask_b32_e64 v187, v187, v71, s[4:5]
	v_cndmask_b32_e64 v188, v80, v76, s[8:9]
	v_cndmask_b32_e64 v189, v81, v77, s[8:9]
	v_cndmask_b32_e64 v190, v82, v78, s[8:9]
	v_cndmask_b32_e64 v191, v83, v79, s[8:9]
	v_cndmask_b32_e64 v188, v188, v72, s[4:5]
	v_cndmask_b32_e64 v189, v189, v73, s[4:5]
	v_cndmask_b32_e64 v190, v190, v74, s[4:5]
	v_cndmask_b32_e64 v191, v191, v75, s[4:5]
	v_pk_fma_f32 v[192:193], v[176:177], v[88:89], v[84:85]
	v_pk_fma_f32 v[194:195], v[178:179], v[90:91], v[86:87]
	v_pk_fma_f32 v[192:193], v[180:181], v[92:93], v[192:193]
	v_pk_fma_f32 v[194:195], v[182:183], v[94:95], v[194:195]
	v_pk_fma_f32 v[192:193], v[184:185], v[96:97], v[192:193]
	v_pk_fma_f32 v[194:195], v[186:187], v[98:99], v[194:195]
	v_pk_fma_f32 v[192:193], v[188:189], v[100:101], v[192:193]
	v_pk_fma_f32 v[194:195], v[190:191], v[102:103], v[194:195]
	v_cvt_pk_bf16_f32 v192, v192, v193
	v_cvt_pk_bf16_f32 v193, v194, v195
	global_store_dwordx2 v104, v[192:193], s[54:55] sc1
	s_nop 1
	s_waitcnt vmcnt(2)
; __device__ __forceinline__ unsigned cvt_pk_bf16(float lo, float hi) { unsigned r; asm volatile("v_cvt_pk_bf16_f32 %0, %1, %2" : "=v"(r) : "v"(lo), "v"(hi)); return r; }
; __global__ void __launch_bounds__(NTHR, 2) hybrid_block_fwd(Args a) {
;     ...
;             const f32x4 h0 = *(const f32x4*)(H), h1 = *(const f32x4*)(H + (rr >= 1 ? LW : 0)), h2 = *(const f32x4*)(H + (rr >= 2 ? 2 * LW : 0));
;             const f32x4 T0 = seq0 ? z : t0, T1 = seq0 ? z : t1, T2 = seq0 ? z : t2;
;             const f32x4 u0 = rr == 0 ? h0 : (rr == 1 ? h1 : h2);
;             const f32x4 u1 = rr == 0 ? T2 : (rr == 1 ? h0 : h1);
;             const f32x4 u2 = rr == 0 ? T1 : (rr == 1 ? T2 : h0);
;             const f32x4 u3 = rr == 0 ? T0 : (rr == 1 ? T1 : T2);
;             const f32x4 v = *(const f32x4*)(lru_conv_b + c4) + *(const f32x4*)(lru_conv_w + c4) * u3 + *(const f32x4*)(lru_conv_w + LW + c4) * u2 + *(const f32x4*)(lru_conv_w + 2 * LW + c4) * u1 + *(const f32x4*)(lru_conv_w + 3 * LW + c4) * u0;
;             u32x2 w; w.x = cvt_pk_bf16(v[0], v[1]); w.y = cvt_pk_bf16(v[2], v[3]);
;             *(u32x2*)(VV + row * LW + c4) = w;
	v_and_b32_e32 v200, 0x7f, v158
	v_cmp_ne_u32_e64 s[0:1], 0, v200
	v_cmp_eq_u32_e64 s[4:5], 0, v157
	v_cmp_eq_u32_e64 s[8:9], 1, v157
	s_nop 1
	v_cndmask_b32_e64 v112, 0, v112, s[0:1]
	v_cndmask_b32_e64 v113, 0, v113, s[0:1]
	v_cndmask_b32_e64 v114, 0, v114, s[0:1]
	v_cndmask_b32_e64 v115, 0, v115, s[0:1]
	v_cndmask_b32_e64 v116, 0, v116, s[0:1]
	v_cndmask_b32_e64 v117, 0, v117, s[0:1]
	v_cndmask_b32_e64 v118, 0, v118, s[0:1]
	v_cndmask_b32_e64 v119, 0, v119, s[0:1]
	v_cndmask_b32_e64 v120, 0, v120, s[0:1]
	v_cndmask_b32_e64 v121, 0, v121, s[0:1]
	v_cndmask_b32_e64 v122, 0, v122, s[0:1]
	v_cndmask_b32_e64 v123, 0, v123, s[0:1]
	v_cndmask_b32_e64 v176, v120, v116, s[8:9]
	v_cndmask_b32_e64 v177, v121, v117, s[8:9]
	v_cndmask_b32_e64 v178, v122, v118, s[8:9]
	v_cndmask_b32_e64 v179, v123, v119, s[8:9]
	v_cndmask_b32_e64 v176, v176, v112, s[4:5]
	v_cndmask_b32_e64 v177, v177, v113, s[4:5]
	v_cndmask_b32_e64 v178, v178, v114, s[4:5]
	v_cndmask_b32_e64 v179, v179, v115, s[4:5]
	v_cndmask_b32_e64 v180, v124, v120, s[8:9]
	v_cndmask_b32_e64 v181, v125, v121, s[8:9]
	v_cndmask_b32_e64 v182, v126, v122, s[8:9]
	v_cndmask_b32_e64 v183, v127, v123, s[8:9]
	v_cndmask_b32_e64 v180, v180, v116, s[4:5]
	v_cndmask_b32_e64 v181, v181, v117, s[4:5]
	v_cndmask_b32_e64 v182, v182, v118, s[4:5]
	v_cndmask_b32_e64 v183, v183, v119, s[4:5]
	v_cndmask_b32_e64 v184, v128, v124, s[8:9]
	v_cndmask_b32_e64 v185, v129, v125, s[8:9]
	v_cndmask_b32_e64 v186, v130, v126, s[8:9]
	v_cndmask_b32_e64 v187, v131, v127, s[8:9]
	v_cndmask_b32_e64 v184, v184, v120, s[4:5]
	v_cndmask_b32_e64 v185, v185, v121, s[4:5]
	v_cndmask_b32_e64 v186, v186, v122, s[4:5]
	v_cndmask_b32_e64 v187, v187, v123, s[4:5]
	v_cndmask_b32_e64 v188, v132, v128, s[8:9]
	v_cndmask_b32_e64 v189, v133, v129, s[8:9]
	v_cndmask_b32_e64 v190, v134, v130, s[8:9]
	v_cndmask_b32_e64 v191, v135, v131, s[8:9]
	v_cndmask_b32_e64 v188, v188, v124, s[4:5]
	v_cndmask_b32_e64 v189, v189, v125, s[4:5]
	v_cndmask_b32_e64 v190, v190, v126, s[4:5]
	v_cndmask_b32_e64 v191, v191, v127, s[4:5]
	v_pk_fma_f32 v[192:193], v[176:177], v[140:141], v[136:137]
	v_pk_fma_f32 v[194:195], v[178:179], v[142:143], v[138:139]
	v_pk_fma_f32 v[192:193], v[180:181], v[144:145], v[192:193]
	v_pk_fma_f32 v[194:195], v[182:183], v[146:147], v[194:195]
	v_pk_fma_f32 v[192:193], v[184:185], v[148:149], v[192:193]
	v_pk_fma_f32 v[194:195], v[186:187], v[150:151], v[194:195]
	v_pk_fma_f32 v[192:193], v[188:189], v[152:153], v[192:193]
	v_pk_fma_f32 v[194:195], v[190:191], v[154:155], v[194:195]
	v_cvt_pk_bf16_f32 v192, v192, v193
	v_cvt_pk_bf16_f32 v193, v194, v195
	global_store_dwordx2 v156, v[192:193], s[54:55] sc1
